# P4 boundary tiles: the eight per-row-group rss loads (each followed by a full wait) replaced by the values already loaded together at the top of the epilogue
# speedup vs baseline: 1.0092x; 1.0023x over previous
;     __device__ __forceinline__ void operator()(f32x4 (&acc)[2][2][4][2], const Unit& u, int wr, int wc, int fr, int fq) const {
;     ...
;                 const int tok = tok0 + ai * 128 + wr * 64 + m * 16 + fr;
;                 if (bnd) {
;                     const bool valid = (tok >= 0) && (tok < MTOK);
;                     float rs = 0.f; if (valid) rs = rsqrtf(rss[tok] * (1.0f / 1024.0f) + EPSV);
; #pragma unroll
;                     for (int bj = 0; bj < 2; ++bj)
; #pragma unroll
;                         for (int n = 0; n < 2; ++n) { f32x4 x = acc[ai][bj][m][n] * rs;
; #pragma unroll
;                             for (int j = 0; j < 4; ++j) x[j] = valid ? x[j] : 0.f;
;                             acc[ai][bj][m][n] = x; }
.LBB0_570:
	s_andn2_b64 vcc, exec, s[0:1]
	s_cbranch_vccnz .LBB0_574
	v_cmp_gt_u32_e32 vcc, s69, v152
	v_mov_b32_e32 v4, 0
	s_and_saveexec_b64 s[0:1], vcc
	s_cbranch_execz .LBB0_573
	v_lshl_add_u64 v[0:1], v[152:153], 2, s[60:61]
	s_mov_b32 s4, 0x800000
	s_waitcnt vmcnt(0)
	v_mov_b32_e32 v0, v248
	v_fmamk_f32 v0, v0, 0x3a800000, v242
	v_mul_f32_e32 v1, 0x4b800000, v0
	v_cmp_gt_f32_e64 s[6:7], s4, v0
	s_nop 1
	v_cndmask_b32_e64 v0, v0, v1, s[6:7]
	v_rsq_f32_e32 v0, v0
	s_nop 0
	v_mul_f32_e32 v1, 0x45800000, v0
	v_cndmask_b32_e64 v4, v0, v1, s[6:7]

;     __device__ __forceinline__ void operator()(f32x4 (&acc)[2][2][4][2], const Unit& u, int wr, int wc, int fr, int fq) const {
;     ...
;                     const bool valid = (tok >= 0) && (tok < MTOK);
;                     float rs = 0.f; if (valid) rs = rsqrtf(rss[tok] * (1.0f / 1024.0f) + EPSV);
.LBB0_589:
	v_cmp_gt_u32_e32 vcc, s69, v128
	v_mov_b32_e32 v130, 0
	s_and_saveexec_b64 s[0:1], vcc
	s_cbranch_execz .LBB0_591
	v_mov_b32_e32 v129, v153
	v_lshl_add_u64 v[128:129], v[128:129], 2, s[60:61]
	s_mov_b32 s4, 0x800000
	s_waitcnt vmcnt(0)
	v_mov_b32_e32 v128, v249
	v_fmamk_f32 v128, v128, 0x3a800000, v242
	v_mul_f32_e32 v129, 0x4b800000, v128
	v_cmp_gt_f32_e64 s[8:9], s4, v128
	s_nop 1
	v_cndmask_b32_e64 v128, v128, v129, s[8:9]
	v_rsq_f32_e32 v128, v128
	s_nop 0
	v_mul_f32_e32 v129, 0x45800000, v128
	v_cndmask_b32_e64 v130, v128, v129, s[8:9]

;     __device__ __forceinline__ void operator()(f32x4 (&acc)[2][2][4][2], const Unit& u, int wr, int wc, int fr, int fq) const {
;     ...
;                     const bool valid = (tok >= 0) && (tok < MTOK);
;                     float rs = 0.f; if (valid) rs = rsqrtf(rss[tok] * (1.0f / 1024.0f) + EPSV);
.LBB0_593:
	v_cmp_gt_u32_e32 vcc, s69, v112
	v_mov_b32_e32 v114, 0
	s_and_saveexec_b64 s[0:1], vcc
	s_cbranch_execz .LBB0_595
	v_mov_b32_e32 v113, v153
	v_lshl_add_u64 v[112:113], v[112:113], 2, s[60:61]
	s_mov_b32 s4, 0x800000
	s_waitcnt vmcnt(0)
	v_mov_b32_e32 v112, v250
	v_fmamk_f32 v112, v112, 0x3a800000, v242
	v_mul_f32_e32 v113, 0x4b800000, v112
	v_cmp_gt_f32_e64 s[8:9], s4, v112
	s_nop 1
	v_cndmask_b32_e64 v112, v112, v113, s[8:9]
	v_rsq_f32_e32 v112, v112
	s_nop 0
	v_mul_f32_e32 v113, 0x45800000, v112
	v_cndmask_b32_e64 v114, v112, v113, s[8:9]

;     __device__ __forceinline__ void operator()(f32x4 (&acc)[2][2][4][2], const Unit& u, int wr, int wc, int fr, int fq) const {
;     ...
;                     const bool valid = (tok >= 0) && (tok < MTOK);
;                     float rs = 0.f; if (valid) rs = rsqrtf(rss[tok] * (1.0f / 1024.0f) + EPSV);
.LBB0_597:
	v_cmp_gt_u32_e32 vcc, s69, v112
	v_mov_b32_e32 v20, 0
	s_and_saveexec_b64 s[0:1], vcc
	s_cbranch_execz .LBB0_599
	v_mov_b32_e32 v113, v153
	v_lshl_add_u64 v[16:17], v[112:113], 2, s[60:61]
	s_mov_b32 s4, 0x800000
	s_waitcnt vmcnt(0)
	v_mov_b32_e32 v16, v251
	v_fmamk_f32 v16, v16, 0x3a800000, v242
	v_mul_f32_e32 v17, 0x4b800000, v16
	v_cmp_gt_f32_e64 s[8:9], s4, v16
	s_nop 1
	v_cndmask_b32_e64 v16, v16, v17, s[8:9]
	v_rsq_f32_e32 v16, v16
	s_nop 0
	v_mul_f32_e32 v17, 0x45800000, v16
	v_cndmask_b32_e64 v20, v16, v17, s[8:9]

;     __device__ __forceinline__ void operator()(f32x4 (&acc)[2][2][4][2], const Unit& u, int wr, int wc, int fr, int fq) const {
;     ...
;                     const bool valid = (tok >= 0) && (tok < MTOK);
;                     float rs = 0.f; if (valid) rs = rsqrtf(rss[tok] * (1.0f / 1024.0f) + EPSV);
.LBB0_601:
	v_cmp_gt_u32_e32 vcc, s69, v112
	v_mov_b32_e32 v12, 0
	s_and_saveexec_b64 s[0:1], vcc
	s_cbranch_execz .LBB0_603
	v_mov_b32_e32 v113, v153
	v_lshl_add_u64 v[8:9], v[112:113], 2, s[60:61]
	s_mov_b32 s4, 0x800000
	s_waitcnt vmcnt(0)
	v_mov_b32_e32 v8, v252
	v_fmamk_f32 v8, v8, 0x3a800000, v242
	v_mul_f32_e32 v9, 0x4b800000, v8
	v_cmp_gt_f32_e64 s[8:9], s4, v8
	s_nop 1
	v_cndmask_b32_e64 v8, v8, v9, s[8:9]
	v_rsq_f32_e32 v8, v8
	s_nop 0
	v_mul_f32_e32 v9, 0x45800000, v8
	v_cndmask_b32_e64 v12, v8, v9, s[8:9]

;     __device__ __forceinline__ void operator()(f32x4 (&acc)[2][2][4][2], const Unit& u, int wr, int wc, int fr, int fq) const {
;     ...
;                     const bool valid = (tok >= 0) && (tok < MTOK);
;                     float rs = 0.f; if (valid) rs = rsqrtf(rss[tok] * (1.0f / 1024.0f) + EPSV);
.LBB0_605:
	v_cmp_gt_u32_e32 vcc, s69, v96
	v_mov_b32_e32 v98, 0
	s_and_saveexec_b64 s[0:1], vcc
	s_cbranch_execz .LBB0_607
	v_mov_b32_e32 v97, v153
	v_lshl_add_u64 v[96:97], v[96:97], 2, s[60:61]
	s_mov_b32 s4, 0x800000
	s_waitcnt vmcnt(0)
	v_mov_b32_e32 v96, v253
	v_fmamk_f32 v96, v96, 0x3a800000, v242
	v_mul_f32_e32 v97, 0x4b800000, v96
	v_cmp_gt_f32_e64 s[8:9], s4, v96
	s_nop 1
	v_cndmask_b32_e64 v96, v96, v97, s[8:9]
	v_rsq_f32_e32 v96, v96
	s_nop 0
	v_mul_f32_e32 v97, 0x45800000, v96
	v_cndmask_b32_e64 v98, v96, v97, s[8:9]

;     __device__ __forceinline__ void operator()(f32x4 (&acc)[2][2][4][2], const Unit& u, int wr, int wc, int fr, int fq) const {
;     ...
;                     const bool valid = (tok >= 0) && (tok < MTOK);
;                     float rs = 0.f; if (valid) rs = rsqrtf(rss[tok] * (1.0f / 1024.0f) + EPSV);
.LBB0_609:
	v_cmp_gt_u32_e32 vcc, s69, v80
	v_mov_b32_e32 v82, 0
	s_and_saveexec_b64 s[0:1], vcc
	s_cbranch_execz .LBB0_611
	v_mov_b32_e32 v81, v153
	v_lshl_add_u64 v[80:81], v[80:81], 2, s[60:61]
	s_mov_b32 s4, 0x800000
	s_waitcnt vmcnt(0)
	v_mov_b32_e32 v80, v229
	v_fmamk_f32 v80, v80, 0x3a800000, v242
	v_mul_f32_e32 v81, 0x4b800000, v80
	v_cmp_gt_f32_e64 s[8:9], s4, v80
	s_nop 1
	v_cndmask_b32_e64 v80, v80, v81, s[8:9]
	v_rsq_f32_e32 v80, v80
	s_nop 0
	v_mul_f32_e32 v81, 0x45800000, v80
	v_cndmask_b32_e64 v82, v80, v81, s[8:9]

;     __device__ __forceinline__ void operator()(f32x4 (&acc)[2][2][4][2], const Unit& u, int wr, int wc, int fr, int fq) const {
;     ...
;                     const bool valid = (tok >= 0) && (tok < MTOK);
;                     float rs = 0.f; if (valid) rs = rsqrtf(rss[tok] * (1.0f / 1024.0f) + EPSV);
.LBB0_613:
	v_cmp_gt_u32_e32 vcc, s69, v80
	v_mov_b32_e32 v28, 0
	s_and_saveexec_b64 s[0:1], vcc
	s_cbranch_execz .LBB0_615
	v_mov_b32_e32 v81, v153
	v_lshl_add_u64 v[24:25], v[80:81], 2, s[60:61]
	s_mov_b32 s4, 0x800000
	s_waitcnt vmcnt(0)
	v_mov_b32_e32 v24, v230
	v_fmamk_f32 v24, v24, 0x3a800000, v242
	v_mul_f32_e32 v25, 0x4b800000, v24
	v_cmp_gt_f32_e64 s[6:7], s4, v24
	s_nop 1
	v_cndmask_b32_e64 v24, v24, v25, s[6:7]
	v_rsq_f32_e32 v24, v24
	s_nop 0
	v_mul_f32_e32 v25, 0x45800000, v24
	v_cndmask_b32_e64 v28, v24, v25, s[6:7]
